# candF + P5a topk S rows: coalesced 1-KiB loads prefetched one row ahead, redistributed through a padded per-wave LDS tile
# speedup vs baseline: 1.0212x; 1.0171x over previous
; #define LAS __attribute__((address_space(3)))
; __device__ __forceinline__ void peer_select(const float* S, const int row, const int lane, LAS float* sv, LAS int* si, LAS float* fvL, LAS int* eL, int& e0o, int& e1o, float& g0o, float& g1o) {
;     ...
;             const int grp = lane >> 2, qtr = lane & 3;
;             float x[32];
;             const float* sp = S + (size_t)row * NPQ + grp * 128 + qtr * 32;
; #pragma unroll
;             for (int k = 0; k < 8; ++k) { const f32x4 v = *(const f32x4*)(sp + 4 * k); x[4 * k] = v[0]; x[4 * k + 1] = v[1]; x[4 * k + 2] = v[2]; x[4 * k + 3] = v[3]; }
; __device__ __forceinline__ void peer_topk_w(const Args& a, LAS unsigned char* lds, const int widx, const int nwtot, const int row_lo, const int row_hi) {
;     const int tid = threadIdx.x, lane = tid & 63;
;     unsigned char* ws = a.ws;
;     const float* S = (const float*)(ws + WS_S);
;     LAS float* sv = (LAS float*)(lds + __builtin_amdgcn_readfirstlane(tid >> 6) * 3072); LAS int* si = (LAS int*)(sv + 256); LAS float* fvL = (LAS float*)(si + 256); LAS int* eL = (LAS int*)(fvL + 128);
;     for (int row = row_lo + widx; row < row_hi; row += nwtot) {
.LBB0_930:
	v_lshrrev_b32_e32 v1, 2, v88
	v_and_b32_e32 v6, 3, v0
	v_lshlrev_b32_e32 v2, 9, v1
	v_mov_b32_e32 v3, 0
	v_lshl_add_u64 v[4:5], s[24:25], 0, v[2:3]
	v_lshlrev_b32_e32 v2, 7, v6
	v_lshl_add_u64 v[4:5], v[4:5], 0, v[2:3]
	s_mov_b64 s[0:1], 0x12146000
	v_lshlrev_b32_e32 v39, 4, v1
	v_lshrrev_b32_e32 v1, 3, v88
	s_mulk_i32 s4, 0xc00
	v_lshl_add_u64 v[34:35], v[4:5], 0, s[0:1]
	v_and_b32_e32 v2, 7, v0
	v_lshlrev_b32_e32 v4, 7, v1
	s_add_i32 s22, s4, 0
	v_lshl_or_b32 v5, v2, 3, v4
	v_cmp_eq_u32_e64 s[10:11], 0, v2
	v_cmp_lt_u32_e64 s[12:13], 1, v2
	v_cmp_lt_u32_e64 s[14:15], 3, v2
	v_lshlrev_b32_e32 v73, 4, v1
	v_lshlrev_b32_e32 v2, 2, v88
	v_mbcnt_lo_u32_b32 v1, -1, 0
	v_lshlrev_b32_e32 v38, 5, v6
	v_add_u32_e32 v74, s22, v2
	v_mov_b32_e32 v89, v3
	v_lshl_add_u64 v[2:3], s[24:25], 0, v[2:3]
	s_mov_b64 s[0:1], 0x1b346000
	v_mbcnt_hi_u32_b32 v1, -1, v1
	v_cmp_eq_u32_e64 s[4:5], 0, v6
	v_cmp_lt_u32_e64 s[6:7], 1, v6
	v_cmp_eq_u32_e64 s[8:9], 3, v6
	v_or_b32_e32 v40, 1, v38
	v_or_b32_e32 v41, 2, v38
	v_or_b32_e32 v42, 3, v38
	v_or_b32_e32 v43, 4, v38
	v_or_b32_e32 v44, 5, v38
	v_or_b32_e32 v45, 6, v38
	v_or_b32_e32 v46, 7, v38
	v_or_b32_e32 v47, 8, v38
	v_or_b32_e32 v48, 9, v38
	v_or_b32_e32 v49, 10, v38
	v_or_b32_e32 v50, 11, v38
	v_or_b32_e32 v51, 12, v38
	v_or_b32_e32 v52, 13, v38
	v_or_b32_e32 v53, 14, v38
	v_or_b32_e32 v54, 15, v38
	v_or_b32_e32 v55, 16, v38
	v_or_b32_e32 v56, 17, v38
	v_or_b32_e32 v57, 18, v38
	v_or_b32_e32 v58, 19, v38
	v_or_b32_e32 v59, 20, v38
	v_or_b32_e32 v60, 21, v38
	v_or_b32_e32 v61, 22, v38
	v_or_b32_e32 v62, 23, v38
	v_or_b32_e32 v63, 24, v38
	v_or_b32_e32 v64, 25, v38
	v_or_b32_e32 v65, 26, v38
	v_or_b32_e32 v66, 27, v38
	v_or_b32_e32 v67, 28, v38
	v_or_b32_e32 v68, 29, v38
	v_or_b32_e32 v69, 30, v38
	v_or_b32_e32 v70, 31, v38
	v_add_u32_e32 v71, s22, v5
	v_add_u32_e32 v72, s22, v4
	v_lshl_add_u64 v[36:37], v[2:3], 0, s[0:1]
	v_lshl_or_b32 v75, v1, 2, 28
	s_mul_i32 s0, s22, 3
	s_add_i32 s0, s0, 0xfffff000
	v_lshrrev_b32_e32 v154, 3, v88
	v_add_u32_e32 v154, v154, v88
	v_lshl_add_u32 v154, v154, 4, s0
	v_lshrrev_b32_e32 v155, 2, v88
	v_mul_u32_u24_e32 v155, 0x240, v155
	v_and_b32_e32 v152, 3, v88
	v_mul_u32_u24_e32 v152, 0x90, v152
	v_add3_u32 v155, v155, v152, s0
	v_lshlrev_b32_e32 v158, 4, v88
	v_mov_b32_e32 v159, 0
	v_lshl_add_u64 v[158:159], s[24:25], 0, v[158:159]
	s_mov_b64 s[0:1], 0x12146000
	v_lshl_add_u64 v[158:159], v[158:159], 0, s[0:1]
	s_ashr_i32 s35, s34, 31
	s_lshl_b64 s[0:1], s[34:35], 13
	v_lshl_add_u64 v[152:153], v[158:159], 0, s[0:1]
	s_add_u32 s0, s0, 0x1000
	s_addc_u32 s1, s1, 0
	v_lshl_add_u64 v[156:157], v[158:159], 0, s[0:1]
	global_load_dwordx4 v[120:123], v[152:153], off
	global_load_dwordx4 v[124:127], v[152:153], off offset:1024
	global_load_dwordx4 v[128:131], v[152:153], off offset:2048
	global_load_dwordx4 v[132:135], v[152:153], off offset:3072
	global_load_dwordx4 v[136:139], v[156:157], off
	global_load_dwordx4 v[140:143], v[156:157], off offset:1024
	global_load_dwordx4 v[144:147], v[156:157], off offset:2048
	global_load_dwordx4 v[148:151], v[156:157], off offset:3072
	s_branch .LBB0_932

; template <int GS> __device__ __forceinline__ float grp_max_f(float v) { v = fmaxf(v, dpp_f<0xB1>(v)); v = fmaxf(v, dpp_f<0x4E>(v)); if (GS == 8) v = fmaxf(v, dpp_f<0x141>(v)); return v; }
; template <int GS> __device__ __forceinline__ float grp_min_f(float v) { v = fminf(v, dpp_f<0xB1>(v)); v = fminf(v, dpp_f<0x4E>(v)); if (GS == 8) v = fminf(v, dpp_f<0x141>(v)); return v; }
; template <int GS> __device__ __forceinline__ void bisect16(const float (&x)[32], float& lo, float& hi) {
;     float mx = x[0], mn = x[0];
; #pragma unroll
;     for (int j = 1; j < 32; ++j) { mx = fmaxf(mx, x[j]); mn = fminf(mn, x[j]); }
;     hi = grp_max_f<GS>(mx); lo = grp_min_f<GS>(mn);
; __device__ __forceinline__ void peer_select(const float* S, const int row, const int lane, LAS float* sv, LAS int* si, LAS float* fvL, LAS int* eL, int& e0o, int& e1o, float& g0o, float& g1o) {
;     ...
;             const float* sp = S + (size_t)row * NPQ + grp * 128 + qtr * 32;
; #pragma unroll
;             for (int k = 0; k < 8; ++k) { const f32x4 v = *(const f32x4*)(sp + 4 * k); x[4 * k] = v[0]; x[4 * k + 1] = v[1]; x[4 * k + 2] = v[2]; x[4 * k + 3] = v[3]; }
;             float lo, hi;
;             bisect16<4>(x, lo, hi);
.LBB0_932:
	s_ashr_i32 s35, s34, 31
	s_waitcnt vmcnt(0)
	ds_write_b128 v154, v[120:123]
	ds_write_b128 v154, v[124:127] offset:1152
	ds_write_b128 v154, v[128:131] offset:2304
	ds_write_b128 v154, v[132:135] offset:3456
	ds_write_b128 v154, v[136:139] offset:4608
	ds_write_b128 v154, v[140:143] offset:5760
	ds_write_b128 v154, v[144:147] offset:6912
	ds_write_b128 v154, v[148:151] offset:8064
	ds_read_b128 v[30:33], v155
	ds_read_b128 v[26:29], v155 offset:16
	ds_read_b128 v[22:25], v155 offset:32
	ds_read_b128 v[18:21], v155 offset:48
	ds_read_b128 v[14:17], v155 offset:64
	ds_read_b128 v[10:13], v155 offset:80
	ds_read_b128 v[6:9], v155 offset:96
	ds_read_b128 v[2:5], v155 offset:112
	s_waitcnt lgkmcnt(0)
	s_add_i32 s0, s34, s2
	s_cmpk_lt_i32 s0, 0x4000
	s_cselect_b32 s0, s0, s34
	s_ashr_i32 s1, s0, 31
	s_lshl_b64 s[0:1], s[0:1], 13
	v_lshl_add_u64 v[152:153], v[158:159], 0, s[0:1]
	s_add_u32 s0, s0, 0x1000
	s_addc_u32 s1, s1, 0
	v_lshl_add_u64 v[156:157], v[158:159], 0, s[0:1]
	global_load_dwordx4 v[120:123], v[152:153], off
	global_load_dwordx4 v[124:127], v[152:153], off offset:1024
	global_load_dwordx4 v[128:131], v[152:153], off offset:2048
	global_load_dwordx4 v[132:135], v[152:153], off offset:3072
	global_load_dwordx4 v[136:139], v[156:157], off
	global_load_dwordx4 v[140:143], v[156:157], off offset:1024
	global_load_dwordx4 v[144:147], v[156:157], off offset:2048
	global_load_dwordx4 v[148:151], v[156:157], off offset:3072
	v_mov_b32_e32 v76, 0
	v_mov_b32_e32 v79, 0
	v_mov_b32_e32 v77, 0
	v_mov_b32_e32 v80, 0
	v_mov_b32_e32 v78, 47
	s_mov_b64 s[0:1], 0
	v_max_f32_e32 v81, v31, v31
	v_max_f32_e32 v82, v30, v30
	v_max_f32_e32 v83, v82, v81
	v_min_f32_e32 v81, v82, v81
	v_max3_f32 v82, v83, v32, v33
	v_min3_f32 v81, v81, v32, v33
	v_max3_f32 v82, v82, v26, v27
	v_min3_f32 v81, v81, v26, v27
	v_max3_f32 v82, v82, v28, v29
	v_min3_f32 v81, v81, v28, v29
	v_max3_f32 v82, v82, v22, v23
	v_min3_f32 v81, v81, v22, v23
	v_max3_f32 v82, v82, v24, v25
	v_min3_f32 v81, v81, v24, v25
	v_max3_f32 v82, v82, v18, v19
	v_min3_f32 v81, v81, v18, v19
	v_max3_f32 v82, v82, v20, v21
	v_min3_f32 v81, v81, v20, v21
	v_max3_f32 v82, v82, v14, v15
	v_min3_f32 v81, v81, v14, v15
	v_max3_f32 v82, v82, v16, v17
	v_min3_f32 v81, v81, v16, v17
	v_max3_f32 v82, v82, v10, v11
	v_min3_f32 v81, v81, v10, v11
	v_max3_f32 v82, v82, v12, v13
	v_min3_f32 v81, v81, v12, v13
	v_max3_f32 v82, v82, v6, v7
	v_min3_f32 v81, v81, v6, v7
	v_max3_f32 v82, v82, v8, v9
	v_min3_f32 v81, v81, v8, v9
	v_max3_f32 v82, v82, v2, v3
	v_min3_f32 v81, v81, v2, v3
	v_max3_f32 v82, v82, v4, v5
	v_min3_f32 v81, v81, v4, v5
	s_nop 0
	v_mov_b32_dpp v76, v82 quad_perm:[1,0,3,2] row_mask:0xf bank_mask:0xf
	v_mov_b32_dpp v79, v81 quad_perm:[1,0,3,2] row_mask:0xf bank_mask:0xf
	v_max_f32_e32 v76, v76, v76
	v_max_f32_e32 v79, v79, v79
	v_max_f32_e32 v76, v82, v76
	v_min_f32_e32 v79, v81, v79
	s_nop 0
	v_mov_b32_dpp v77, v76 quad_perm:[2,3,0,1] row_mask:0xf bank_mask:0xf
	v_mov_b32_dpp v80, v79 quad_perm:[2,3,0,1] row_mask:0xf bank_mask:0xf
	v_max_f32_e32 v77, v77, v77
	v_max_f32_e32 v80, v80, v80
	v_max_f32_e32 v76, v76, v77
	v_min_f32_e32 v77, v79, v80
